# NSA selected branch rewritten block-major per wave: union of 8 queries blocks, 16 MFMA columns = 4 queries x 4 heads, one fetch per distinct block
# speedup vs baseline: 1.0806x; 1.0707x over previous
.LBB0_3923:
	s_lshl_b64 s[14:15], 1, s10
	s_or_b64 s[14:15], s[14:15], s[12:13]
	v_cmp_le_u64_e32 vcc, s[14:15], v[14:15]
	s_bcnt1_i32_b64 s16, vcc
	v_cmp_le_u64_e32 vcc, s[14:15], v[12:13]
	s_bcnt1_i32_b64 s17, vcc
	v_cmp_le_u64_e32 vcc, s[14:15], v[6:7]
	s_add_i32 s16, s17, s16
	s_bcnt1_i32_b64 s17, vcc
	v_cmp_le_u64_e32 vcc, s[14:15], v[4:5]
	s_add_i32 s16, s16, s17
	s_bcnt1_i32_b64 s17, vcc
	s_add_i32 s16, s16, s17
	s_cmp_gt_u32 s16, 15
	s_cselect_b32 s13, s15, s13
	s_cselect_b32 s12, s14, s12
	s_cmp_lg_u32 s16, 16
	s_cselect_b64 s[14:15], -1, 0
	s_cmp_lg_u32 s10, 0
	s_cselect_b64 s[16:17], -1, 0
	s_and_b64 s[14:15], s[14:15], s[16:17]
	s_add_u32 s10, s10, -1
	s_addc_u32 s11, s11, -1
	s_and_b64 vcc, exec, s[14:15]
	s_cbranch_vccnz .LBB0_3923
	v_cmp_le_u64_e32 vcc, s[12:13], v[14:15]
	s_nop 1
	v_and_b32_e32 v9, vcc_lo, v2
	v_and_b32_e32 v8, vcc_hi, v1
	v_bcnt_u32_b32 v9, v9, 0
	v_bcnt_u32_b32 v8, v8, v9
	v_mov_b32_e32 v9, v0
	v_cmp_gt_u64_e64 s[10:11], 16, v[8:9]
	s_and_b64 s[14:15], vcc, s[10:11]
	s_and_saveexec_b64 s[10:11], s[14:15]
	v_lshl_add_u32 v8, v8, 2, s61
	ds_write_b32 v8, v3
	s_or_b64 exec, exec, s[10:11]
	s_bcnt1_i32_b64 s14, vcc
	v_cmp_le_u64_e32 vcc, s[12:13], v[12:13]
	s_nop 1
	v_and_b32_e32 v8, vcc_lo, v2
	v_and_b32_e32 v3, vcc_hi, v1
	v_bcnt_u32_b32 v8, v8, 0
	v_bcnt_u32_b32 v3, v3, v8
	v_add_u32_e32 v3, s14, v3
	v_cmp_gt_u32_e64 s[10:11], 16, v3
	s_and_b64 s[16:17], vcc, s[10:11]
	s_and_saveexec_b64 s[10:11], s[16:17]
	v_lshl_add_u32 v3, v3, 2, s61
	ds_write_b32 v3, v11
	s_or_b64 exec, exec, s[10:11]
	s_bcnt1_i32_b64 s10, vcc
	v_cmp_le_u64_e32 vcc, s[12:13], v[6:7]
	s_add_i32 s14, s10, s14
	s_nop 0
	v_and_b32_e32 v6, vcc_lo, v2
	v_and_b32_e32 v3, vcc_hi, v1
	v_bcnt_u32_b32 v6, v6, 0
	v_bcnt_u32_b32 v3, v3, v6
	v_add_u32_e32 v3, s14, v3
	v_cmp_gt_u32_e64 s[10:11], 16, v3
	s_and_b64 s[16:17], vcc, s[10:11]
	s_and_saveexec_b64 s[10:11], s[16:17]
	v_lshl_add_u32 v3, v3, 2, s61
	ds_write_b32 v3, v20
	s_or_b64 exec, exec, s[10:11]
	s_bcnt1_i32_b64 s10, vcc
	v_cmp_le_u64_e32 vcc, s[12:13], v[4:5]
	s_add_i32 s14, s14, s10
	s_nop 0
	v_and_b32_e32 v2, vcc_lo, v2
	v_and_b32_e32 v1, vcc_hi, v1
	v_bcnt_u32_b32 v2, v2, 0
	v_bcnt_u32_b32 v1, v1, v2
	v_add_u32_e32 v1, s14, v1
	v_cmp_gt_u32_e64 s[10:11], 16, v1
	s_and_b64 s[12:13], vcc, s[10:11]
	s_and_saveexec_b64 s[10:11], s[12:13]
	v_lshl_add_u32 v1, v1, 2, s61
	ds_write_b32 v1, v21
	s_or_b64 exec, exec, s[10:11]
	v_cmp_gt_i32_e32 vcc, s6, v49
	v_mov_b32_e32 v1, s81
	v_mov_b32_e32 v2, s79
	v_cndmask_b32_e32 v3, v1, v2, vcc
	v_mov_b32_e32 v1, s80
	v_mov_b32_e32 v2, s78
	v_cndmask_b32_e32 v2, v1, v2, vcc
	v_and_b32_e32 v4, 0xff0, v124
	v_mov_b32_e32 v5, v0
	v_lshl_add_u64 v[6:7], v[2:3], 0, v[4:5]
	v_cndmask_b32_e64 v1, v174, 0, vcc
	v_mov_b32_e32 v2, s49
	s_movk_i32 s10, 0xfe
	v_add3_u32 v1, s6, v1, v4
	v_sub_u32_e64 v8, s10, v2 clamp
	global_load_dwordx4 v[2:5], v[6:7], off
	s_lshl_b32 s54, s48, 12
	s_mov_b32 s87, s55
	s_lshl_b64 s[12:13], s[86:87], 11
	s_add_u32 s10, s38, s12
	s_addc_u32 s11, s39, s13
	s_waitcnt vmcnt(0)
	ds_write_b128 v1, v[2:5]
	v_lshlrev_b32_e32 v2, 12, v8
	v_mov_b32_e32 v3, v0
	v_lshl_add_u64 v[2:3], v[6:7], 0, v[2:3]
	global_load_dwordx4 v[2:5], v[2:3], off
	s_waitcnt vmcnt(0)
	ds_write_b128 v1, v[2:5] offset:8192
	v_lshl_add_u64 v[2:3], v[6:7], 0, s[54:55]
	global_load_dwordx4 v[2:5], v[2:3], off
	v_mov_b32_e32 v7, v0
	s_waitcnt vmcnt(0)
	ds_write_b128 v1, v[2:5] offset:16384
	v_and_b32_e32 v4, 48, v49
	v_lshlrev_b32_e32 v2, 1, v121
	v_mov_b32_e32 v3, v0
	v_lshl_add_u64 v[2:3], s[10:11], 0, v[2:3]
	v_lshlrev_b32_e32 v6, 1, v4
	v_lshl_add_u64 v[6:7], v[2:3], 0, v[6:7]
	v_mov_b32_e32 v2, v0
	v_mov_b32_e32 v3, v0
	v_mov_b32_e32 v1, v0
	v_mov_b64_e32 v[72:73], v[2:3]
	v_cmp_gt_u32_e64 s[10:11], 4, v122
	v_mov_b64_e32 v[70:71], v[0:1]
	s_waitcnt lgkmcnt(0)
	s_barrier
	v_and_b32_e32 v1, 63, v160
	v_lshrrev_b32_e32 v203, 6, v160
	v_and_b32_e32 v201, 15, v1
	v_lshrrev_b32_e32 v187, 4, v1
	v_readfirstlane_b32 s22, v203
	v_lshrrev_b32_e32 v165, 2, v201
	v_mov_b32_e32 v193, 0
	v_lshlrev_b32_e32 v192, 6, v201
	v_lshl_or_b32 v192, v187, 4, v192
	v_lshl_add_u64 v[166:167], s[78:79], 0, v[192:193]
	v_lshl_add_u64 v[190:191], s[80:81], 0, v[192:193]
	v_add_u32_e32 v188, 0x100, v192
	v_xor_b32_e32 v197, 16, v1
	v_lshlrev_b32_e32 v197, 2, v197
	v_xor_b32_e32 v198, 32, v1
	v_lshlrev_b32_e32 v198, 2, v198
	v_mov_b32_e32 v199, 0xf149f2ca
	v_mov_b32_e32 v200, 0x7149f2ca
	s_lshl_b32 s23, s22, 9
	s_add_i32 s23, s23, 0x20900
	v_lshl_add_u32 v203, v1, 2, s23
	ds_read_b32 v252, v203
	ds_read_b32 v253, v203 offset:256
	s_lshl_b32 s23, s22, 10
	s_add_i32 s23, s23, 0x10900
	v_mov_b32_e32 v244, 0
	v_mov_b32_e32 v245, 0
	v_mov_b32_e32 v246, 0
	v_mov_b32_e32 v247, 0
	v_lshl_add_u32 v204, v1, 4, s23
	ds_write_b128 v204, v[244:247]
	v_lshrrev_b32_e32 v248, 4, v1
	v_lshlrev_b32_e64 v249, v248, 1
	v_lshlrev_b32_e32 v250, 4, v249
	s_waitcnt lgkmcnt(0)
	v_cmp_le_i32_e32 vcc, 0, v252
	v_lshl_add_u32 v203, v252, 2, s23
	s_and_saveexec_b64 s[12:13], vcc
	ds_or_b32 v203, v249
	s_mov_b64 exec, s[12:13]
	v_cmp_le_i32_e32 vcc, 0, v253
	v_lshl_add_u32 v203, v253, 2, s23
	s_and_saveexec_b64 s[12:13], vcc
	ds_or_b32 v203, v250
	s_mov_b64 exec, s[12:13]
	v_lshl_add_u32 v203, v1, 2, s23
	s_waitcnt lgkmcnt(0)
	ds_read_b32 v244, v203
	ds_read_b32 v245, v203 offset:256
	ds_read_b32 v246, v203 offset:512
	ds_read_b32 v247, v203 offset:768
	s_lshl_b32 s23, s22, 12
	s_add_i32 s23, s23, 0x8900
	v_lshl_add_u32 v207, v201, 7, s23
	v_lshl_add_u32 v207, v187, 3, v207
	s_lshl_b32 s21, s22, 3
	s_add_i32 s20, s48, -1
	v_add_u32_e32 v206, s21, v165
	s_lshl_b32 s54, s48, 6
	s_add_i32 s54, s54, s21
	s_and_b32 s101, s65, 3
	s_lshl_b32 s12, s54, 11
	s_lshl_b32 s23, s101, 9
	s_add_i32 s12, s12, s23
	s_add_u32 s12, s38, s12
	s_addc_u32 s13, s39, 0
	v_and_b32_e32 v192, 3, v201
	v_lshlrev_b32_e32 v192, 7, v192
	v_lshl_or_b32 v192, v187, 5, v192
	v_lshl_or_b32 v192, v165, 11, v192
	v_lshl_add_u64 v[192:193], s[12:13], 0, v[192:193]
	global_load_dwordx4 v[212:215], v[192:193], off
	global_load_dwordx4 v[216:219], v[192:193], off offset:16
	v_add_co_u32_e32 v192, vcc, 0x2000, v192
	s_nop 1
	v_addc_co_u32_e32 v193, vcc, 0, v193, vcc
	global_load_dwordx4 v[220:223], v[192:193], off
	global_load_dwordx4 v[224:227], v[192:193], off offset:16
	s_mul_i32 s12, s54, 0xc0
	s_lshl_b32 s23, s101, 4
	s_add_i32 s12, s12, s23
	s_add_i32 s12, s12, 0xf400040
	s_add_u32 s12, s38, s12
	s_addc_u32 s13, s39, 0
	v_and_b32_e32 v204, 3, v201
	v_mul_u32_u24_e32 v248, 0xc0, v165
	v_mov_b32_e32 v249, 0
	v_lshl_add_u32 v248, v204, 2, v248
	v_lshl_add_u64 v[248:249], s[12:13], 0, v[248:249]
	global_load_dword v208, v[248:249], off
	global_load_dword v148, v[248:249], off offset:768
	v_lshlrev_b32_e32 v187, 2, v187
	s_mov_b32 s13, 0
	s_waitcnt lgkmcnt(0)
	v_lshl_or_b32 v164, v245, 8, v244
	v_lshl_or_b32 v164, v246, 16, v164
	v_lshl_or_b32 v164, v247, 24, v164
	v_and_b32_e32 v203, 0xff, v164
	v_cmp_ne_u32_e64 s[98:99], 0, v203
	s_mov_b32 s100, 0
	v_mov_b32_e32 v158, v199
	v_mov_b32_e32 v159, 0
	v_mov_b32_e32 v102, 0
	v_mov_b32_e32 v103, 0
	v_mov_b32_e32 v104, 0
	v_mov_b32_e32 v105, 0
	v_mov_b32_e32 v106, 0
	v_mov_b32_e32 v107, 0
	v_mov_b32_e32 v108, 0
	v_mov_b32_e32 v109, 0
	v_mov_b32_e32 v110, 0
	v_mov_b32_e32 v111, 0
	v_mov_b32_e32 v112, 0
	v_mov_b32_e32 v113, 0
	v_mov_b32_e32 v114, 0
	v_mov_b32_e32 v115, 0
	v_mov_b32_e32 v116, 0
	v_mov_b32_e32 v117, 0
	v_mov_b32_e32 v162, v199
	v_mov_b32_e32 v163, 0
	v_mov_b32_e32 v118, 0
	v_mov_b32_e32 v119, 0
	v_mov_b32_e32 v120, 0
	v_mov_b32_e32 v121, 0
	v_mov_b32_e32 v122, 0
	v_mov_b32_e32 v123, 0
	v_mov_b32_e32 v124, 0
	v_mov_b32_e32 v125, 0
	v_mov_b32_e32 v136, 0
	v_mov_b32_e32 v137, 0
	v_mov_b32_e32 v138, 0
	v_mov_b32_e32 v139, 0
	v_mov_b32_e32 v140, 0
	v_mov_b32_e32 v141, 0
	v_mov_b32_e32 v142, 0
	v_mov_b32_e32 v143, 0
.Lsb_na_1:
	s_cmp_eq_u64 s[98:99], 0
	s_cbranch_scc0 .Lsb_nh_2
	s_cmp_ge_u32 s100, 3
	s_cbranch_scc1 .Lsb_ne_3
	s_add_i32 s100, s100, 1
	s_lshl_b32 s101, s100, 3
	v_lshrrev_b32_e32 v203, s101, v164
	v_and_b32_e32 v203, 0xff, v203
	v_cmp_ne_u32_e64 s[98:99], 0, v203
	s_nop 3
	s_branch .Lsb_na_1
.Lsb_ne_3:
	s_mov_b32 s14, -1
	s_mov_b32 s17, 0
	s_branch .Lsb_nd_4
.Lsb_nh_2:
	s_ff1_i32_b64 s101, s[98:99]
	s_bitset0_b64 s[98:99], s101
	v_readlane_b32 s17, v164, s101
	s_lshl_b32 s14, s100, 6
	s_or_b32 s14, s14, s101
	s_lshl_b32 s101, s100, 3
	s_lshr_b32 s17, s17, s101
	s_and_b32 s17, s17, 0xff
.Lsb_nd_4:
.Lsb_na_5:
	s_cmp_eq_u64 s[98:99], 0
	s_cbranch_scc0 .Lsb_nh_6
	s_cmp_ge_u32 s100, 3
	s_cbranch_scc1 .Lsb_ne_7
	s_add_i32 s100, s100, 1
	s_lshl_b32 s101, s100, 3
	v_lshrrev_b32_e32 v203, s101, v164
	v_and_b32_e32 v203, 0xff, v203
	v_cmp_ne_u32_e64 s[98:99], 0, v203
	s_nop 3
	s_branch .Lsb_na_5
.Lsb_ne_7:
	s_mov_b32 s15, -1
	s_mov_b32 s18, 0
	s_branch .Lsb_nd_8
.Lsb_nh_6:
	s_ff1_i32_b64 s101, s[98:99]
	s_bitset0_b64 s[98:99], s101
	v_readlane_b32 s18, v164, s101
	s_lshl_b32 s15, s100, 6
	s_or_b32 s15, s15, s101
	s_lshl_b32 s101, s100, 3
	s_lshr_b32 s18, s18, s101
	s_and_b32 s18, s18, 0xff
.Lsb_nd_8:
	s_mov_b32 s24, 0
	s_cmp_lt_i32 s14, 0
	s_cbranch_scc1 .Lsb_fd_9
	s_mov_b32 s23, 0
	s_cmp_eq_u32 s14, 0
	s_cbranch_scc1 .Lsb_fl_10
	s_movk_i32 s23, 0x4000
	s_cmp_eq_u32 s14, s48
	s_cbranch_scc1 .Lsb_fl_10
	s_movk_i32 s23, 0x2000
	s_cmp_eq_u32 s14, s20
	s_cbranch_scc1 .Lsb_fl_10
	s_lshl_b32 s12, s14, 12
	s_mov_b32 s24, 1
	v_lshl_add_u64 v[192:193], v[166:167], 0, s[12:13]
	global_load_dwordx4 v[2:5], v[192:193], off
	global_load_dwordx4 v[6:9], v[192:193], off offset:1024
	global_load_dwordx4 v[10:13], v[192:193], off offset:2048
	global_load_dwordx4 v[14:17], v[192:193], off offset:3072
	v_lshl_add_u64 v[192:193], v[190:191], 0, s[12:13]
	global_load_dwordx4 v[18:21], v[192:193], off
	global_load_dwordx4 v[22:25], v[192:193], off offset:1024
	global_load_dwordx4 v[26:29], v[192:193], off offset:2048
	global_load_dwordx4 v[30:33], v[192:193], off offset:3072
	s_branch .Lsb_fd_9
.Lsb_fl_10:
	v_add_u32_e32 v189, s23, v188
	ds_read_b128 v[2:5], v189
	ds_read_b128 v[6:9], v189 offset:1024
	ds_read_b128 v[10:13], v189 offset:2048
	ds_read_b128 v[14:17], v189 offset:3072
	ds_read_b128 v[18:21], v189 offset:4096
	ds_read_b128 v[22:25], v189 offset:5120
	ds_read_b128 v[26:29], v189 offset:6144
	ds_read_b128 v[30:33], v189 offset:7168
	s_waitcnt lgkmcnt(0)
.Lsb_fd_9:
	s_mov_b32 s54, s24
	s_mov_b32 s24, 0
	s_cmp_lt_i32 s15, 0
	s_cbranch_scc1 .Lsb_fd_11
	s_mov_b32 s23, 0
	s_cmp_eq_u32 s15, 0
	s_cbranch_scc1 .Lsb_fl_12
	s_movk_i32 s23, 0x4000
	s_cmp_eq_u32 s15, s48
	s_cbranch_scc1 .Lsb_fl_12
	s_movk_i32 s23, 0x2000
	s_cmp_eq_u32 s15, s20
	s_cbranch_scc1 .Lsb_fl_12
	s_lshl_b32 s12, s15, 12
	s_mov_b32 s24, 1
	v_lshl_add_u64 v[192:193], v[166:167], 0, s[12:13]
	global_load_dwordx4 v[34:37], v[192:193], off
	global_load_dwordx4 v[38:41], v[192:193], off offset:1024
	global_load_dwordx4 v[42:45], v[192:193], off offset:2048
	global_load_dwordx4 v[46:49], v[192:193], off offset:3072
	v_lshl_add_u64 v[192:193], v[190:191], 0, s[12:13]
	global_load_dwordx4 v[50:53], v[192:193], off
	global_load_dwordx4 v[54:57], v[192:193], off offset:1024
	global_load_dwordx4 v[58:61], v[192:193], off offset:2048
	global_load_dwordx4 v[62:65], v[192:193], off offset:3072
	s_branch .Lsb_fd_11
.Lsb_fl_12:
	v_add_u32_e32 v189, s23, v188
	ds_read_b128 v[34:37], v189
	ds_read_b128 v[38:41], v189 offset:1024
	ds_read_b128 v[42:45], v189 offset:2048
	ds_read_b128 v[46:49], v189 offset:3072
	ds_read_b128 v[50:53], v189 offset:4096
	ds_read_b128 v[54:57], v189 offset:5120
	ds_read_b128 v[58:61], v189 offset:6144
	ds_read_b128 v[62:65], v189 offset:7168
	s_waitcnt lgkmcnt(0)
.Lsb_fd_11:
	s_add_i32 s22, s54, s24
	s_cmp_eq_u32 s22, 2
	s_cbranch_scc1 .Lsb_w16_14
	s_cmp_eq_u32 s22, 1
	s_cbranch_scc1 .Lsb_w8_13
	s_waitcnt vmcnt(0)
	s_branch .Lsb_wd_15

.Lsb_wd_15:
	v_lshlrev_b32_e32 v248, 16, v212
	v_and_b32_e32 v249, 0xffff0000, v212
	v_mul_f32_e32 v248, 0x40b17218, v248
	v_mul_f32_e32 v249, 0x40b17218, v249
	v_cvt_pk_fp8_f32 v144, v248, v249
	v_lshlrev_b32_e32 v250, 16, v213
	v_and_b32_e32 v251, 0xffff0000, v213
	v_mul_f32_e32 v250, 0x40b17218, v250
	v_mul_f32_e32 v251, 0x40b17218, v251
	v_cvt_pk_fp8_f32 v144, v250, v251 op_sel:[0,0,1]
	v_lshlrev_b32_e32 v248, 16, v214
	v_and_b32_e32 v249, 0xffff0000, v214
	v_mul_f32_e32 v248, 0x40b17218, v248
	v_mul_f32_e32 v249, 0x40b17218, v249
	v_cvt_pk_fp8_f32 v145, v248, v249
	v_lshlrev_b32_e32 v250, 16, v215
	v_and_b32_e32 v251, 0xffff0000, v215
	v_mul_f32_e32 v250, 0x40b17218, v250
	v_mul_f32_e32 v251, 0x40b17218, v251
	v_cvt_pk_fp8_f32 v145, v250, v251 op_sel:[0,0,1]
	v_lshlrev_b32_e32 v248, 16, v216
	v_and_b32_e32 v249, 0xffff0000, v216
	v_mul_f32_e32 v248, 0x40b17218, v248
	v_mul_f32_e32 v249, 0x40b17218, v249
	v_cvt_pk_fp8_f32 v146, v248, v249
	v_lshlrev_b32_e32 v250, 16, v217
	v_and_b32_e32 v251, 0xffff0000, v217
	v_mul_f32_e32 v250, 0x40b17218, v250
	v_mul_f32_e32 v251, 0x40b17218, v251
	v_cvt_pk_fp8_f32 v146, v250, v251 op_sel:[0,0,1]
	v_lshlrev_b32_e32 v248, 16, v218
	v_and_b32_e32 v249, 0xffff0000, v218
	v_mul_f32_e32 v248, 0x40b17218, v248
	v_mul_f32_e32 v249, 0x40b17218, v249
	v_cvt_pk_fp8_f32 v147, v248, v249
	v_lshlrev_b32_e32 v250, 16, v219
	v_and_b32_e32 v251, 0xffff0000, v219
	v_mul_f32_e32 v250, 0x40b17218, v250
	v_mul_f32_e32 v251, 0x40b17218, v251
	v_cvt_pk_fp8_f32 v147, v250, v251 op_sel:[0,0,1]
	v_lshlrev_b32_e32 v248, 16, v220
	v_and_b32_e32 v249, 0xffff0000, v220
	v_mul_f32_e32 v248, 0x40b17218, v248
	v_mul_f32_e32 v249, 0x40b17218, v249
	v_cvt_pk_fp8_f32 v150, v248, v249
	v_lshlrev_b32_e32 v250, 16, v221
	v_and_b32_e32 v251, 0xffff0000, v221
	v_mul_f32_e32 v250, 0x40b17218, v250
	v_mul_f32_e32 v251, 0x40b17218, v251
	v_cvt_pk_fp8_f32 v150, v250, v251 op_sel:[0,0,1]
	v_lshlrev_b32_e32 v248, 16, v222
	v_and_b32_e32 v249, 0xffff0000, v222
	v_mul_f32_e32 v248, 0x40b17218, v248
	v_mul_f32_e32 v249, 0x40b17218, v249
	v_cvt_pk_fp8_f32 v151, v248, v249
	v_lshlrev_b32_e32 v250, 16, v223
	v_and_b32_e32 v251, 0xffff0000, v223
	v_mul_f32_e32 v250, 0x40b17218, v250
	v_mul_f32_e32 v251, 0x40b17218, v251
	v_cvt_pk_fp8_f32 v151, v250, v251 op_sel:[0,0,1]
	v_lshlrev_b32_e32 v248, 16, v224
	v_and_b32_e32 v249, 0xffff0000, v224
	v_mul_f32_e32 v248, 0x40b17218, v248
	v_mul_f32_e32 v249, 0x40b17218, v249
	v_cvt_pk_fp8_f32 v152, v248, v249
	v_lshlrev_b32_e32 v250, 16, v225
	v_and_b32_e32 v251, 0xffff0000, v225
	v_mul_f32_e32 v250, 0x40b17218, v250
	v_mul_f32_e32 v251, 0x40b17218, v251
	v_cvt_pk_fp8_f32 v152, v250, v251 op_sel:[0,0,1]
	v_lshlrev_b32_e32 v248, 16, v226
	v_and_b32_e32 v249, 0xffff0000, v226
	v_mul_f32_e32 v248, 0x40b17218, v248
	v_mul_f32_e32 v249, 0x40b17218, v249
	v_cvt_pk_fp8_f32 v153, v248, v249
	v_lshlrev_b32_e32 v250, 16, v227
	v_and_b32_e32 v251, 0xffff0000, v227
	v_mul_f32_e32 v250, 0x40b17218, v250
	v_mul_f32_e32 v251, 0x40b17218, v251
	v_cvt_pk_fp8_f32 v153, v250, v251 op_sel:[0,0,1]
.Lsb_step0:
	s_cmp_lt_i32 s14, 0
	s_cbranch_scc1 .Lsb_exit

.Lsb_ne_18:
	s_mov_b32 s16, -1
	s_mov_b32 s19, 0
	s_branch .Lsb_nd_19
.Lsb_nh_17:
	s_ff1_i32_b64 s101, s[98:99]
	s_bitset0_b64 s[98:99], s101
	v_readlane_b32 s19, v164, s101
	s_lshl_b32 s16, s100, 6
	s_or_b32 s16, s16, s101
	s_lshl_b32 s101, s100, 3
	s_lshr_b32 s19, s19, s101
	s_and_b32 s19, s19, 0xff
.Lsb_nd_19:
	s_mov_b32 s25, 0
	s_cmp_lt_i32 s16, 0
	s_cbranch_scc1 .Lsb_fd_20
	s_mov_b32 s23, 0
	s_cmp_eq_u32 s16, 0
	s_cbranch_scc1 .Lsb_fl_21
	s_movk_i32 s23, 0x4000
	s_cmp_eq_u32 s16, s48
	s_cbranch_scc1 .Lsb_fl_21
	s_movk_i32 s23, 0x2000
	s_cmp_eq_u32 s16, s20
	s_cbranch_scc1 .Lsb_fl_21
	s_lshl_b32 s12, s16, 12
	s_mov_b32 s25, 1
	v_lshl_add_u64 v[192:193], v[166:167], 0, s[12:13]
	global_load_dwordx4 v[212:215], v[192:193], off
	global_load_dwordx4 v[216:219], v[192:193], off offset:1024
	global_load_dwordx4 v[220:223], v[192:193], off offset:2048
	global_load_dwordx4 v[224:227], v[192:193], off offset:3072
	v_lshl_add_u64 v[192:193], v[190:191], 0, s[12:13]
	global_load_dwordx4 v[228:231], v[192:193], off
	global_load_dwordx4 v[232:235], v[192:193], off offset:1024
	global_load_dwordx4 v[236:239], v[192:193], off offset:2048
	global_load_dwordx4 v[240:243], v[192:193], off offset:3072
	s_branch .Lsb_fd_20
.Lsb_fl_21:
	v_add_u32_e32 v189, s23, v188
	ds_read_b128 v[212:215], v189
	ds_read_b128 v[216:219], v189 offset:1024
	ds_read_b128 v[220:223], v189 offset:2048
	ds_read_b128 v[224:227], v189 offset:3072
	ds_read_b128 v[228:231], v189 offset:4096
	ds_read_b128 v[232:235], v189 offset:5120
	ds_read_b128 v[236:239], v189 offset:6144
	ds_read_b128 v[240:243], v189 offset:7168
	s_waitcnt lgkmcnt(0)
.Lsb_fd_20:
	s_add_i32 s22, s24, s25
	s_cmp_eq_u32 s22, 2
	s_cbranch_scc1 .Lsb_w16_23
	s_cmp_eq_u32 s22, 1
	s_cbranch_scc1 .Lsb_w8_22
	s_waitcnt vmcnt(0)
	s_branch .Lsb_wd_24

.Lsb_wd_24:
	s_bfe_u32 s22, s17, 0x40000
	s_cmp_eq_u32 s22, 0
	s_cbranch_scc1 .Lsb_sg_25
	s_lshr_b32 s22, s17, 0
	v_lshrrev_b32_e64 v203, v165, s22
	v_and_b32_e32 v203, 1, v203
	v_cmp_eq_u32_e64 s[10:11], 1, v203
	s_setprio 1
	v_mfma_f32_16x16x32_fp8_fp8 v[66:69], v[2:3], v[144:145], 0
	v_mfma_f32_16x16x32_fp8_fp8 v[70:73], v[6:7], v[144:145], 0
	v_mfma_f32_16x16x32_fp8_fp8 v[74:77], v[10:11], v[144:145], 0
	v_mfma_f32_16x16x32_fp8_fp8 v[78:81], v[14:15], v[144:145], 0
	v_mfma_f32_16x16x32_fp8_fp8 v[66:69], v[4:5], v[146:147], v[66:69]
	v_mfma_f32_16x16x32_fp8_fp8 v[70:73], v[8:9], v[146:147], v[70:73]
	v_mfma_f32_16x16x32_fp8_fp8 v[74:77], v[12:13], v[146:147], v[74:77]
	v_mfma_f32_16x16x32_fp8_fp8 v[78:81], v[16:17], v[146:147], v[78:81]
	s_setprio 0
	v_cndmask_b32_e64 v205, v200, v158, s[10:11]
	s_cmp_lg_u32 s14, s48
	s_nop 6
	s_cbranch_scc1 .Lsb_nm_26
	v_sub_u32_e32 v244, v206, v187
	v_cmp_gt_i32_e32 vcc, 0, v244
	v_cmp_gt_i32_e64 s[22:23], 1, v244
	s_nop 0
	v_cndmask_b32_e32 v66, v66, v199, vcc
	v_cndmask_b32_e64 v67, v67, v199, s[22:23]
	v_cmp_gt_i32_e32 vcc, 2, v244
	v_cmp_gt_i32_e64 s[22:23], 3, v244
	s_nop 0
	v_cndmask_b32_e32 v68, v68, v199, vcc
	v_cndmask_b32_e64 v69, v69, v199, s[22:23]
	v_sub_u32_e32 v244, v206, v187
	v_subrev_u32_e32 v244, 16, v244
	v_cmp_gt_i32_e32 vcc, 0, v244
	v_cmp_gt_i32_e64 s[22:23], 1, v244
	s_nop 0
	v_cndmask_b32_e32 v70, v70, v199, vcc
	v_cndmask_b32_e64 v71, v71, v199, s[22:23]
	v_cmp_gt_i32_e32 vcc, 2, v244
	v_cmp_gt_i32_e64 s[22:23], 3, v244
	s_nop 0
	v_cndmask_b32_e32 v72, v72, v199, vcc
	v_cndmask_b32_e64 v73, v73, v199, s[22:23]
	v_sub_u32_e32 v244, v206, v187
	v_subrev_u32_e32 v244, 32, v244
	v_cmp_gt_i32_e32 vcc, 0, v244
	v_cmp_gt_i32_e64 s[22:23], 1, v244
	s_nop 0
	v_cndmask_b32_e32 v74, v74, v199, vcc
	v_cndmask_b32_e64 v75, v75, v199, s[22:23]
	v_cmp_gt_i32_e32 vcc, 2, v244
	v_cmp_gt_i32_e64 s[22:23], 3, v244
	s_nop 0
	v_cndmask_b32_e32 v76, v76, v199, vcc
	v_cndmask_b32_e64 v77, v77, v199, s[22:23]
	v_sub_u32_e32 v244, v206, v187
	v_subrev_u32_e32 v244, 48, v244
	v_cmp_gt_i32_e32 vcc, 0, v244
	v_cmp_gt_i32_e64 s[22:23], 1, v244
	s_nop 0
	v_cndmask_b32_e32 v78, v78, v199, vcc
	v_cndmask_b32_e64 v79, v79, v199, s[22:23]
	v_cmp_gt_i32_e32 vcc, 2, v244
	v_cmp_gt_i32_e64 s[22:23], 3, v244
	s_nop 0
	v_cndmask_b32_e32 v80, v80, v199, vcc
	v_cndmask_b32_e64 v81, v81, v199, s[22:23]
.Lsb_nm_26:
	v_max3_f32 v202, v66, v67, v68
	v_max3_f32 v203, v69, v70, v71
	v_max3_f32 v202, v202, v72, v73
	v_max3_f32 v203, v203, v74, v75
	v_max3_f32 v202, v202, v76, v77
	v_max3_f32 v203, v203, v78, v79
	v_max3_f32 v202, v202, v80, v81
	v_max_f32_e32 v202, v202, v203
	v_mul_f32_e32 v202, 0x3e38aa3b, v202
	v_cndmask_b32_e64 v202, v199, v202, s[10:11]
	v_add_f32_e32 v203, 0x41000000, v158
	v_cmp_gt_f32_e32 vcc, v202, v203
	s_cbranch_vccz .Lsb_nr_27
	ds_bpermute_b32 v203, v197, v202
	s_waitcnt lgkmcnt(0)
	v_max_f32_e32 v203, v202, v203
	ds_bpermute_b32 v204, v198, v203
	s_waitcnt lgkmcnt(0)
	v_max_f32_e32 v203, v203, v204
	v_max_f32_e32 v203, v158, v203
	v_sub_f32_e32 v204, v158, v203
	v_exp_f32_e32 v204, v204
	v_mov_b32_e32 v158, v203
	s_nop 0
	v_mul_f32_e32 v159, v159, v204
	v_mul_f32_e32 v102, v102, v204
	v_mul_f32_e32 v103, v103, v204
	v_mul_f32_e32 v104, v104, v204
	v_mul_f32_e32 v105, v105, v204
	v_mul_f32_e32 v106, v106, v204
	v_mul_f32_e32 v107, v107, v204
	v_mul_f32_e32 v108, v108, v204
	v_mul_f32_e32 v109, v109, v204
	v_mul_f32_e32 v110, v110, v204
	v_mul_f32_e32 v111, v111, v204
	v_mul_f32_e32 v112, v112, v204
	v_mul_f32_e32 v113, v113, v204
	v_mul_f32_e32 v114, v114, v204
	v_mul_f32_e32 v115, v115, v204
	v_mul_f32_e32 v116, v116, v204
	v_mul_f32_e32 v117, v117, v204
	v_cndmask_b32_e64 v205, v200, v158, s[10:11]
.Lsb_nr_27:
	s_mov_b32 s22, 0x3e38aa3b
	v_fma_f32 v66, v66, s22, -v205
	v_fma_f32 v67, v67, s22, -v205
	v_fma_f32 v68, v68, s22, -v205
	v_fma_f32 v69, v69, s22, -v205
	v_fma_f32 v70, v70, s22, -v205
	v_fma_f32 v71, v71, s22, -v205
	v_fma_f32 v72, v72, s22, -v205
	v_fma_f32 v73, v73, s22, -v205
	v_fma_f32 v74, v74, s22, -v205
	v_fma_f32 v75, v75, s22, -v205
	v_fma_f32 v76, v76, s22, -v205
	v_fma_f32 v77, v77, s22, -v205
	v_fma_f32 v78, v78, s22, -v205
	v_fma_f32 v79, v79, s22, -v205
	v_fma_f32 v80, v80, s22, -v205
	v_fma_f32 v81, v81, s22, -v205
	v_exp_f32_e32 v66, v66
	v_exp_f32_e32 v67, v67
	v_exp_f32_e32 v68, v68
	v_exp_f32_e32 v69, v69
	v_exp_f32_e32 v70, v70
	v_exp_f32_e32 v71, v71
	v_exp_f32_e32 v72, v72
	v_exp_f32_e32 v73, v73
	v_exp_f32_e32 v74, v74
	v_exp_f32_e32 v75, v75
	v_exp_f32_e32 v76, v76
	v_exp_f32_e32 v77, v77
	v_exp_f32_e32 v78, v78
	v_exp_f32_e32 v79, v79
	v_exp_f32_e32 v80, v80
	v_exp_f32_e32 v81, v81
	v_add_f32_e32 v244, v66, v70
	v_add_f32_e32 v245, v67, v71
	v_add_f32_e32 v246, v68, v72
	v_add_f32_e32 v247, v69, v73
	v_add_f32_e32 v248, v74, v78
	v_add_f32_e32 v249, v75, v79
	v_add_f32_e32 v250, v76, v80
	v_add_f32_e32 v251, v77, v81
	v_add_f32_e32 v244, v244, v248
	v_add_f32_e32 v245, v245, v249
	v_add_f32_e32 v246, v246, v250
	v_add_f32_e32 v247, v247, v251
	v_cvt_pk_fp8_f32 v154, v66, v67
	v_cvt_pk_fp8_f32 v155, v70, v71
	v_cvt_pk_fp8_f32 v156, v74, v75
	v_cvt_pk_fp8_f32 v157, v78, v79
	v_add_f32_e32 v244, v244, v245
	v_cvt_pk_fp8_f32 v154, v68, v69 op_sel:[0,0,1]
	v_cvt_pk_fp8_f32 v155, v72, v73 op_sel:[0,0,1]
	v_cvt_pk_fp8_f32 v156, v76, v77 op_sel:[0,0,1]
	v_cvt_pk_fp8_f32 v157, v80, v81 op_sel:[0,0,1]
	v_add_f32_e32 v246, v246, v247
	v_add_f32_e32 v244, v244, v246
	v_add_f32_e32 v159, v159, v244
	s_setprio 1
	v_mfma_f32_16x16x32_fp8_fp8 v[102:105], v[18:19], v[154:155], v[102:105]
	v_mfma_f32_16x16x32_fp8_fp8 v[106:109], v[22:23], v[154:155], v[106:109]
	v_mfma_f32_16x16x32_fp8_fp8 v[110:113], v[26:27], v[154:155], v[110:113]
	v_mfma_f32_16x16x32_fp8_fp8 v[114:117], v[30:31], v[154:155], v[114:117]
	v_mfma_f32_16x16x32_fp8_fp8 v[102:105], v[20:21], v[156:157], v[102:105]
	v_mfma_f32_16x16x32_fp8_fp8 v[106:109], v[24:25], v[156:157], v[106:109]
	v_mfma_f32_16x16x32_fp8_fp8 v[110:113], v[28:29], v[156:157], v[110:113]
	v_mfma_f32_16x16x32_fp8_fp8 v[114:117], v[32:33], v[156:157], v[114:117]
	s_setprio 0
.Lsb_sg_25:
	s_bfe_u32 s22, s17, 0x40004
	s_cmp_eq_u32 s22, 0
	s_cbranch_scc1 .Lsb_sg_28
	s_lshr_b32 s22, s17, 4
	v_lshrrev_b32_e64 v203, v165, s22
	v_and_b32_e32 v203, 1, v203
	v_cmp_eq_u32_e64 s[10:11], 1, v203
	s_setprio 1
	v_mfma_f32_16x16x32_fp8_fp8 v[66:69], v[2:3], v[150:151], 0
	v_mfma_f32_16x16x32_fp8_fp8 v[70:73], v[6:7], v[150:151], 0
	v_mfma_f32_16x16x32_fp8_fp8 v[74:77], v[10:11], v[150:151], 0
	v_mfma_f32_16x16x32_fp8_fp8 v[78:81], v[14:15], v[150:151], 0
	v_mfma_f32_16x16x32_fp8_fp8 v[66:69], v[4:5], v[152:153], v[66:69]
	v_mfma_f32_16x16x32_fp8_fp8 v[70:73], v[8:9], v[152:153], v[70:73]
	v_mfma_f32_16x16x32_fp8_fp8 v[74:77], v[12:13], v[152:153], v[74:77]
	v_mfma_f32_16x16x32_fp8_fp8 v[78:81], v[16:17], v[152:153], v[78:81]
	s_setprio 0
	v_cndmask_b32_e64 v205, v200, v162, s[10:11]
	s_cmp_lg_u32 s14, s48
	s_nop 6
	s_cbranch_scc1 .Lsb_nm_29
	v_sub_u32_e32 v244, v206, v187
	v_subrev_u32_e32 v244, -4, v244
	v_cmp_gt_i32_e32 vcc, 0, v244
	v_cmp_gt_i32_e64 s[22:23], 1, v244
	s_nop 0
	v_cndmask_b32_e32 v66, v66, v199, vcc
	v_cndmask_b32_e64 v67, v67, v199, s[22:23]
	v_cmp_gt_i32_e32 vcc, 2, v244
	v_cmp_gt_i32_e64 s[22:23], 3, v244
	s_nop 0
	v_cndmask_b32_e32 v68, v68, v199, vcc
	v_cndmask_b32_e64 v69, v69, v199, s[22:23]
	v_sub_u32_e32 v244, v206, v187
	v_subrev_u32_e32 v244, 12, v244
	v_cmp_gt_i32_e32 vcc, 0, v244
	v_cmp_gt_i32_e64 s[22:23], 1, v244
	s_nop 0
	v_cndmask_b32_e32 v70, v70, v199, vcc
	v_cndmask_b32_e64 v71, v71, v199, s[22:23]
	v_cmp_gt_i32_e32 vcc, 2, v244
	v_cmp_gt_i32_e64 s[22:23], 3, v244
	s_nop 0
	v_cndmask_b32_e32 v72, v72, v199, vcc
	v_cndmask_b32_e64 v73, v73, v199, s[22:23]
	v_sub_u32_e32 v244, v206, v187
	v_subrev_u32_e32 v244, 28, v244
	v_cmp_gt_i32_e32 vcc, 0, v244
	v_cmp_gt_i32_e64 s[22:23], 1, v244
	s_nop 0
	v_cndmask_b32_e32 v74, v74, v199, vcc
	v_cndmask_b32_e64 v75, v75, v199, s[22:23]
	v_cmp_gt_i32_e32 vcc, 2, v244
	v_cmp_gt_i32_e64 s[22:23], 3, v244
	s_nop 0
	v_cndmask_b32_e32 v76, v76, v199, vcc
	v_cndmask_b32_e64 v77, v77, v199, s[22:23]
	v_sub_u32_e32 v244, v206, v187
	v_subrev_u32_e32 v244, 44, v244
	v_cmp_gt_i32_e32 vcc, 0, v244
	v_cmp_gt_i32_e64 s[22:23], 1, v244
	s_nop 0
	v_cndmask_b32_e32 v78, v78, v199, vcc
	v_cndmask_b32_e64 v79, v79, v199, s[22:23]
	v_cmp_gt_i32_e32 vcc, 2, v244
	v_cmp_gt_i32_e64 s[22:23], 3, v244
	s_nop 0
	v_cndmask_b32_e32 v80, v80, v199, vcc
	v_cndmask_b32_e64 v81, v81, v199, s[22:23]
.Lsb_nm_29:
	v_max3_f32 v202, v66, v67, v68
	v_max3_f32 v203, v69, v70, v71
	v_max3_f32 v202, v202, v72, v73
	v_max3_f32 v203, v203, v74, v75
	v_max3_f32 v202, v202, v76, v77
	v_max3_f32 v203, v203, v78, v79
	v_max3_f32 v202, v202, v80, v81
	v_max_f32_e32 v202, v202, v203
	v_mul_f32_e32 v202, 0x3e38aa3b, v202
	v_cndmask_b32_e64 v202, v199, v202, s[10:11]
	v_add_f32_e32 v203, 0x41000000, v162
	v_cmp_gt_f32_e32 vcc, v202, v203
	s_cbranch_vccz .Lsb_nr_30
	ds_bpermute_b32 v203, v197, v202
	s_waitcnt lgkmcnt(0)
	v_max_f32_e32 v203, v202, v203
	ds_bpermute_b32 v204, v198, v203
	s_waitcnt lgkmcnt(0)
	v_max_f32_e32 v203, v203, v204
	v_max_f32_e32 v203, v162, v203
	v_sub_f32_e32 v204, v162, v203
	v_exp_f32_e32 v204, v204
	v_mov_b32_e32 v162, v203
	s_nop 0
	v_mul_f32_e32 v163, v163, v204
	v_mul_f32_e32 v118, v118, v204
	v_mul_f32_e32 v119, v119, v204
	v_mul_f32_e32 v120, v120, v204
	v_mul_f32_e32 v121, v121, v204
	v_mul_f32_e32 v122, v122, v204
	v_mul_f32_e32 v123, v123, v204
	v_mul_f32_e32 v124, v124, v204
	v_mul_f32_e32 v125, v125, v204
	v_mul_f32_e32 v136, v136, v204
	v_mul_f32_e32 v137, v137, v204
	v_mul_f32_e32 v138, v138, v204
	v_mul_f32_e32 v139, v139, v204
	v_mul_f32_e32 v140, v140, v204
	v_mul_f32_e32 v141, v141, v204
	v_mul_f32_e32 v142, v142, v204
	v_mul_f32_e32 v143, v143, v204
	v_cndmask_b32_e64 v205, v200, v162, s[10:11]
.Lsb_nr_30:
	s_mov_b32 s22, 0x3e38aa3b
	v_fma_f32 v66, v66, s22, -v205
	v_fma_f32 v67, v67, s22, -v205
	v_fma_f32 v68, v68, s22, -v205
	v_fma_f32 v69, v69, s22, -v205
	v_fma_f32 v70, v70, s22, -v205
	v_fma_f32 v71, v71, s22, -v205
	v_fma_f32 v72, v72, s22, -v205
	v_fma_f32 v73, v73, s22, -v205
	v_fma_f32 v74, v74, s22, -v205
	v_fma_f32 v75, v75, s22, -v205
	v_fma_f32 v76, v76, s22, -v205
	v_fma_f32 v77, v77, s22, -v205
	v_fma_f32 v78, v78, s22, -v205
	v_fma_f32 v79, v79, s22, -v205
	v_fma_f32 v80, v80, s22, -v205
	v_fma_f32 v81, v81, s22, -v205
	v_exp_f32_e32 v66, v66
	v_exp_f32_e32 v67, v67
	v_exp_f32_e32 v68, v68
	v_exp_f32_e32 v69, v69
	v_exp_f32_e32 v70, v70
	v_exp_f32_e32 v71, v71
	v_exp_f32_e32 v72, v72
	v_exp_f32_e32 v73, v73
	v_exp_f32_e32 v74, v74
	v_exp_f32_e32 v75, v75
	v_exp_f32_e32 v76, v76
	v_exp_f32_e32 v77, v77
	v_exp_f32_e32 v78, v78
	v_exp_f32_e32 v79, v79
	v_exp_f32_e32 v80, v80
	v_exp_f32_e32 v81, v81
	v_add_f32_e32 v244, v66, v70
	v_add_f32_e32 v245, v67, v71
	v_add_f32_e32 v246, v68, v72
	v_add_f32_e32 v247, v69, v73
	v_add_f32_e32 v248, v74, v78
	v_add_f32_e32 v249, v75, v79
	v_add_f32_e32 v250, v76, v80
	v_add_f32_e32 v251, v77, v81
	v_add_f32_e32 v244, v244, v248
	v_add_f32_e32 v245, v245, v249
	v_add_f32_e32 v246, v246, v250
	v_add_f32_e32 v247, v247, v251
	v_cvt_pk_fp8_f32 v154, v66, v67
	v_cvt_pk_fp8_f32 v155, v70, v71
	v_cvt_pk_fp8_f32 v156, v74, v75
	v_cvt_pk_fp8_f32 v157, v78, v79
	v_add_f32_e32 v244, v244, v245
	v_cvt_pk_fp8_f32 v154, v68, v69 op_sel:[0,0,1]
	v_cvt_pk_fp8_f32 v155, v72, v73 op_sel:[0,0,1]
	v_cvt_pk_fp8_f32 v156, v76, v77 op_sel:[0,0,1]
	v_cvt_pk_fp8_f32 v157, v80, v81 op_sel:[0,0,1]
	v_add_f32_e32 v246, v246, v247
	v_add_f32_e32 v244, v244, v246
	v_add_f32_e32 v163, v163, v244
	s_setprio 1
	v_mfma_f32_16x16x32_fp8_fp8 v[118:121], v[18:19], v[154:155], v[118:121]
	v_mfma_f32_16x16x32_fp8_fp8 v[122:125], v[22:23], v[154:155], v[122:125]
	v_mfma_f32_16x16x32_fp8_fp8 v[136:139], v[26:27], v[154:155], v[136:139]
	v_mfma_f32_16x16x32_fp8_fp8 v[140:143], v[30:31], v[154:155], v[140:143]
	v_mfma_f32_16x16x32_fp8_fp8 v[118:121], v[20:21], v[156:157], v[118:121]
	v_mfma_f32_16x16x32_fp8_fp8 v[122:125], v[24:25], v[156:157], v[122:125]
	v_mfma_f32_16x16x32_fp8_fp8 v[136:139], v[28:29], v[156:157], v[136:139]
	v_mfma_f32_16x16x32_fp8_fp8 v[140:143], v[32:33], v[156:157], v[140:143]
	s_setprio 0
.Lsb_sg_28:
	s_mov_b32 s14, s15
	s_mov_b32 s15, s16
	s_mov_b32 s17, s18
	s_mov_b32 s18, s19
	s_mov_b32 s24, s25

.Lsb_nd_34:
	s_mov_b32 s25, 0
	s_cmp_lt_i32 s16, 0
	s_cbranch_scc1 .Lsb_fd_35
	s_mov_b32 s23, 0
	s_cmp_eq_u32 s16, 0
	s_cbranch_scc1 .Lsb_fl_36
	s_movk_i32 s23, 0x4000
	s_cmp_eq_u32 s16, s48
	s_cbranch_scc1 .Lsb_fl_36
	s_movk_i32 s23, 0x2000
	s_cmp_eq_u32 s16, s20
	s_cbranch_scc1 .Lsb_fl_36
	s_lshl_b32 s12, s16, 12
	s_mov_b32 s25, 1
	v_lshl_add_u64 v[192:193], v[166:167], 0, s[12:13]
	global_load_dwordx4 v[2:5], v[192:193], off
	global_load_dwordx4 v[6:9], v[192:193], off offset:1024
	global_load_dwordx4 v[10:13], v[192:193], off offset:2048
	global_load_dwordx4 v[14:17], v[192:193], off offset:3072
	v_lshl_add_u64 v[192:193], v[190:191], 0, s[12:13]
	global_load_dwordx4 v[18:21], v[192:193], off
	global_load_dwordx4 v[22:25], v[192:193], off offset:1024
	global_load_dwordx4 v[26:29], v[192:193], off offset:2048
	global_load_dwordx4 v[30:33], v[192:193], off offset:3072
	s_branch .Lsb_fd_35

.Lsb_wd_39:
	s_bfe_u32 s22, s17, 0x40000
	s_cmp_eq_u32 s22, 0
	s_cbranch_scc1 .Lsb_sg_40
	s_lshr_b32 s22, s17, 0
	v_lshrrev_b32_e64 v203, v165, s22
	v_and_b32_e32 v203, 1, v203
	v_cmp_eq_u32_e64 s[10:11], 1, v203
	s_setprio 1
	v_mfma_f32_16x16x32_fp8_fp8 v[66:69], v[34:35], v[144:145], 0
	v_mfma_f32_16x16x32_fp8_fp8 v[70:73], v[38:39], v[144:145], 0
	v_mfma_f32_16x16x32_fp8_fp8 v[74:77], v[42:43], v[144:145], 0
	v_mfma_f32_16x16x32_fp8_fp8 v[78:81], v[46:47], v[144:145], 0
	v_mfma_f32_16x16x32_fp8_fp8 v[66:69], v[36:37], v[146:147], v[66:69]
	v_mfma_f32_16x16x32_fp8_fp8 v[70:73], v[40:41], v[146:147], v[70:73]
	v_mfma_f32_16x16x32_fp8_fp8 v[74:77], v[44:45], v[146:147], v[74:77]
	v_mfma_f32_16x16x32_fp8_fp8 v[78:81], v[48:49], v[146:147], v[78:81]
	s_setprio 0
	v_cndmask_b32_e64 v205, v200, v158, s[10:11]
	s_cmp_lg_u32 s14, s48
	s_nop 6
	s_cbranch_scc1 .Lsb_nm_41
	v_sub_u32_e32 v244, v206, v187
	v_cmp_gt_i32_e32 vcc, 0, v244
	v_cmp_gt_i32_e64 s[22:23], 1, v244
	s_nop 0
	v_cndmask_b32_e32 v66, v66, v199, vcc
	v_cndmask_b32_e64 v67, v67, v199, s[22:23]
	v_cmp_gt_i32_e32 vcc, 2, v244
	v_cmp_gt_i32_e64 s[22:23], 3, v244
	s_nop 0
	v_cndmask_b32_e32 v68, v68, v199, vcc
	v_cndmask_b32_e64 v69, v69, v199, s[22:23]
	v_sub_u32_e32 v244, v206, v187
	v_subrev_u32_e32 v244, 16, v244
	v_cmp_gt_i32_e32 vcc, 0, v244
	v_cmp_gt_i32_e64 s[22:23], 1, v244
	s_nop 0
	v_cndmask_b32_e32 v70, v70, v199, vcc
	v_cndmask_b32_e64 v71, v71, v199, s[22:23]
	v_cmp_gt_i32_e32 vcc, 2, v244
	v_cmp_gt_i32_e64 s[22:23], 3, v244
	s_nop 0
	v_cndmask_b32_e32 v72, v72, v199, vcc
	v_cndmask_b32_e64 v73, v73, v199, s[22:23]
	v_sub_u32_e32 v244, v206, v187
	v_subrev_u32_e32 v244, 32, v244
	v_cmp_gt_i32_e32 vcc, 0, v244
	v_cmp_gt_i32_e64 s[22:23], 1, v244
	s_nop 0
	v_cndmask_b32_e32 v74, v74, v199, vcc
	v_cndmask_b32_e64 v75, v75, v199, s[22:23]
	v_cmp_gt_i32_e32 vcc, 2, v244
	v_cmp_gt_i32_e64 s[22:23], 3, v244
	s_nop 0
	v_cndmask_b32_e32 v76, v76, v199, vcc
	v_cndmask_b32_e64 v77, v77, v199, s[22:23]
	v_sub_u32_e32 v244, v206, v187
	v_subrev_u32_e32 v244, 48, v244
	v_cmp_gt_i32_e32 vcc, 0, v244
	v_cmp_gt_i32_e64 s[22:23], 1, v244
	s_nop 0
	v_cndmask_b32_e32 v78, v78, v199, vcc
	v_cndmask_b32_e64 v79, v79, v199, s[22:23]
	v_cmp_gt_i32_e32 vcc, 2, v244
	v_cmp_gt_i32_e64 s[22:23], 3, v244
	s_nop 0
	v_cndmask_b32_e32 v80, v80, v199, vcc
	v_cndmask_b32_e64 v81, v81, v199, s[22:23]

.Lsb_nr_42:
	s_mov_b32 s22, 0x3e38aa3b
	v_fma_f32 v66, v66, s22, -v205
	v_fma_f32 v67, v67, s22, -v205
	v_fma_f32 v68, v68, s22, -v205
	v_fma_f32 v69, v69, s22, -v205
	v_fma_f32 v70, v70, s22, -v205
	v_fma_f32 v71, v71, s22, -v205
	v_fma_f32 v72, v72, s22, -v205
	v_fma_f32 v73, v73, s22, -v205
	v_fma_f32 v74, v74, s22, -v205
	v_fma_f32 v75, v75, s22, -v205
	v_fma_f32 v76, v76, s22, -v205
	v_fma_f32 v77, v77, s22, -v205
	v_fma_f32 v78, v78, s22, -v205
	v_fma_f32 v79, v79, s22, -v205
	v_fma_f32 v80, v80, s22, -v205
	v_fma_f32 v81, v81, s22, -v205
	v_exp_f32_e32 v66, v66
	v_exp_f32_e32 v67, v67
	v_exp_f32_e32 v68, v68
	v_exp_f32_e32 v69, v69
	v_exp_f32_e32 v70, v70
	v_exp_f32_e32 v71, v71
	v_exp_f32_e32 v72, v72
	v_exp_f32_e32 v73, v73
	v_exp_f32_e32 v74, v74
	v_exp_f32_e32 v75, v75
	v_exp_f32_e32 v76, v76
	v_exp_f32_e32 v77, v77
	v_exp_f32_e32 v78, v78
	v_exp_f32_e32 v79, v79
	v_exp_f32_e32 v80, v80
	v_exp_f32_e32 v81, v81
	v_add_f32_e32 v244, v66, v70
	v_add_f32_e32 v245, v67, v71
	v_add_f32_e32 v246, v68, v72
	v_add_f32_e32 v247, v69, v73
	v_add_f32_e32 v248, v74, v78
	v_add_f32_e32 v249, v75, v79
	v_add_f32_e32 v250, v76, v80
	v_add_f32_e32 v251, v77, v81
	v_add_f32_e32 v244, v244, v248
	v_add_f32_e32 v245, v245, v249
	v_add_f32_e32 v246, v246, v250
	v_add_f32_e32 v247, v247, v251
	v_cvt_pk_fp8_f32 v154, v66, v67
	v_cvt_pk_fp8_f32 v155, v70, v71
	v_cvt_pk_fp8_f32 v156, v74, v75
	v_cvt_pk_fp8_f32 v157, v78, v79
	v_add_f32_e32 v244, v244, v245
	v_cvt_pk_fp8_f32 v154, v68, v69 op_sel:[0,0,1]
	v_cvt_pk_fp8_f32 v155, v72, v73 op_sel:[0,0,1]
	v_cvt_pk_fp8_f32 v156, v76, v77 op_sel:[0,0,1]
	v_cvt_pk_fp8_f32 v157, v80, v81 op_sel:[0,0,1]
	v_add_f32_e32 v246, v246, v247
	v_add_f32_e32 v244, v244, v246
	v_add_f32_e32 v159, v159, v244
	s_setprio 1
	v_mfma_f32_16x16x32_fp8_fp8 v[102:105], v[50:51], v[154:155], v[102:105]
	v_mfma_f32_16x16x32_fp8_fp8 v[106:109], v[54:55], v[154:155], v[106:109]
	v_mfma_f32_16x16x32_fp8_fp8 v[110:113], v[58:59], v[154:155], v[110:113]
	v_mfma_f32_16x16x32_fp8_fp8 v[114:117], v[62:63], v[154:155], v[114:117]
	v_mfma_f32_16x16x32_fp8_fp8 v[102:105], v[52:53], v[156:157], v[102:105]
	v_mfma_f32_16x16x32_fp8_fp8 v[106:109], v[56:57], v[156:157], v[106:109]
	v_mfma_f32_16x16x32_fp8_fp8 v[110:113], v[60:61], v[156:157], v[110:113]
	v_mfma_f32_16x16x32_fp8_fp8 v[114:117], v[64:65], v[156:157], v[114:117]
	s_setprio 0
.Lsb_sg_40:
	s_bfe_u32 s22, s17, 0x40004
	s_cmp_eq_u32 s22, 0
	s_cbranch_scc1 .Lsb_sg_43
	s_lshr_b32 s22, s17, 4
	v_lshrrev_b32_e64 v203, v165, s22
	v_and_b32_e32 v203, 1, v203
	v_cmp_eq_u32_e64 s[10:11], 1, v203
	s_setprio 1
	v_mfma_f32_16x16x32_fp8_fp8 v[66:69], v[34:35], v[150:151], 0
	v_mfma_f32_16x16x32_fp8_fp8 v[70:73], v[38:39], v[150:151], 0
	v_mfma_f32_16x16x32_fp8_fp8 v[74:77], v[42:43], v[150:151], 0
	v_mfma_f32_16x16x32_fp8_fp8 v[78:81], v[46:47], v[150:151], 0
	v_mfma_f32_16x16x32_fp8_fp8 v[66:69], v[36:37], v[152:153], v[66:69]
	v_mfma_f32_16x16x32_fp8_fp8 v[70:73], v[40:41], v[152:153], v[70:73]
	v_mfma_f32_16x16x32_fp8_fp8 v[74:77], v[44:45], v[152:153], v[74:77]
	v_mfma_f32_16x16x32_fp8_fp8 v[78:81], v[48:49], v[152:153], v[78:81]
	s_setprio 0
	v_cndmask_b32_e64 v205, v200, v162, s[10:11]
	s_cmp_lg_u32 s14, s48
	s_nop 6
	s_cbranch_scc1 .Lsb_nm_44
	v_sub_u32_e32 v244, v206, v187
	v_subrev_u32_e32 v244, -4, v244
	v_cmp_gt_i32_e32 vcc, 0, v244
	v_cmp_gt_i32_e64 s[22:23], 1, v244
	s_nop 0
	v_cndmask_b32_e32 v66, v66, v199, vcc
	v_cndmask_b32_e64 v67, v67, v199, s[22:23]
	v_cmp_gt_i32_e32 vcc, 2, v244
	v_cmp_gt_i32_e64 s[22:23], 3, v244
	s_nop 0
	v_cndmask_b32_e32 v68, v68, v199, vcc
	v_cndmask_b32_e64 v69, v69, v199, s[22:23]
	v_sub_u32_e32 v244, v206, v187
	v_subrev_u32_e32 v244, 12, v244
	v_cmp_gt_i32_e32 vcc, 0, v244
	v_cmp_gt_i32_e64 s[22:23], 1, v244
	s_nop 0
	v_cndmask_b32_e32 v70, v70, v199, vcc
	v_cndmask_b32_e64 v71, v71, v199, s[22:23]
	v_cmp_gt_i32_e32 vcc, 2, v244
	v_cmp_gt_i32_e64 s[22:23], 3, v244
	s_nop 0
	v_cndmask_b32_e32 v72, v72, v199, vcc
	v_cndmask_b32_e64 v73, v73, v199, s[22:23]
	v_sub_u32_e32 v244, v206, v187
	v_subrev_u32_e32 v244, 28, v244
	v_cmp_gt_i32_e32 vcc, 0, v244
	v_cmp_gt_i32_e64 s[22:23], 1, v244
	s_nop 0
	v_cndmask_b32_e32 v74, v74, v199, vcc
	v_cndmask_b32_e64 v75, v75, v199, s[22:23]
	v_cmp_gt_i32_e32 vcc, 2, v244
	v_cmp_gt_i32_e64 s[22:23], 3, v244
	s_nop 0
	v_cndmask_b32_e32 v76, v76, v199, vcc
	v_cndmask_b32_e64 v77, v77, v199, s[22:23]
	v_sub_u32_e32 v244, v206, v187
	v_subrev_u32_e32 v244, 44, v244
	v_cmp_gt_i32_e32 vcc, 0, v244
	v_cmp_gt_i32_e64 s[22:23], 1, v244
	s_nop 0
	v_cndmask_b32_e32 v78, v78, v199, vcc
	v_cndmask_b32_e64 v79, v79, v199, s[22:23]
	v_cmp_gt_i32_e32 vcc, 2, v244
	v_cmp_gt_i32_e64 s[22:23], 3, v244
	s_nop 0
	v_cndmask_b32_e32 v80, v80, v199, vcc
	v_cndmask_b32_e64 v81, v81, v199, s[22:23]

.Lsb_nr_45:
	s_mov_b32 s22, 0x3e38aa3b
	v_fma_f32 v66, v66, s22, -v205
	v_fma_f32 v67, v67, s22, -v205
	v_fma_f32 v68, v68, s22, -v205
	v_fma_f32 v69, v69, s22, -v205
	v_fma_f32 v70, v70, s22, -v205
	v_fma_f32 v71, v71, s22, -v205
	v_fma_f32 v72, v72, s22, -v205
	v_fma_f32 v73, v73, s22, -v205
	v_fma_f32 v74, v74, s22, -v205
	v_fma_f32 v75, v75, s22, -v205
	v_fma_f32 v76, v76, s22, -v205
	v_fma_f32 v77, v77, s22, -v205
	v_fma_f32 v78, v78, s22, -v205
	v_fma_f32 v79, v79, s22, -v205
	v_fma_f32 v80, v80, s22, -v205
	v_fma_f32 v81, v81, s22, -v205
	v_exp_f32_e32 v66, v66
	v_exp_f32_e32 v67, v67
	v_exp_f32_e32 v68, v68
	v_exp_f32_e32 v69, v69
	v_exp_f32_e32 v70, v70
	v_exp_f32_e32 v71, v71
	v_exp_f32_e32 v72, v72
	v_exp_f32_e32 v73, v73
	v_exp_f32_e32 v74, v74
	v_exp_f32_e32 v75, v75
	v_exp_f32_e32 v76, v76
	v_exp_f32_e32 v77, v77
	v_exp_f32_e32 v78, v78
	v_exp_f32_e32 v79, v79
	v_exp_f32_e32 v80, v80
	v_exp_f32_e32 v81, v81
	v_add_f32_e32 v244, v66, v70
	v_add_f32_e32 v245, v67, v71
	v_add_f32_e32 v246, v68, v72
	v_add_f32_e32 v247, v69, v73
	v_add_f32_e32 v248, v74, v78
	v_add_f32_e32 v249, v75, v79
	v_add_f32_e32 v250, v76, v80
	v_add_f32_e32 v251, v77, v81
	v_add_f32_e32 v244, v244, v248
	v_add_f32_e32 v245, v245, v249
	v_add_f32_e32 v246, v246, v250
	v_add_f32_e32 v247, v247, v251
	v_cvt_pk_fp8_f32 v154, v66, v67
	v_cvt_pk_fp8_f32 v155, v70, v71
	v_cvt_pk_fp8_f32 v156, v74, v75
	v_cvt_pk_fp8_f32 v157, v78, v79
	v_add_f32_e32 v244, v244, v245
	v_cvt_pk_fp8_f32 v154, v68, v69 op_sel:[0,0,1]
	v_cvt_pk_fp8_f32 v155, v72, v73 op_sel:[0,0,1]
	v_cvt_pk_fp8_f32 v156, v76, v77 op_sel:[0,0,1]
	v_cvt_pk_fp8_f32 v157, v80, v81 op_sel:[0,0,1]
	v_add_f32_e32 v246, v246, v247
	v_add_f32_e32 v244, v244, v246
	v_add_f32_e32 v163, v163, v244
	s_setprio 1
	v_mfma_f32_16x16x32_fp8_fp8 v[118:121], v[50:51], v[154:155], v[118:121]
	v_mfma_f32_16x16x32_fp8_fp8 v[122:125], v[54:55], v[154:155], v[122:125]
	v_mfma_f32_16x16x32_fp8_fp8 v[136:139], v[58:59], v[154:155], v[136:139]
	v_mfma_f32_16x16x32_fp8_fp8 v[140:143], v[62:63], v[154:155], v[140:143]
	v_mfma_f32_16x16x32_fp8_fp8 v[118:121], v[52:53], v[156:157], v[118:121]
	v_mfma_f32_16x16x32_fp8_fp8 v[122:125], v[56:57], v[156:157], v[122:125]
	v_mfma_f32_16x16x32_fp8_fp8 v[136:139], v[60:61], v[156:157], v[136:139]
	v_mfma_f32_16x16x32_fp8_fp8 v[140:143], v[64:65], v[156:157], v[140:143]
	s_setprio 0

.Lsb_nd_49:
	s_mov_b32 s25, 0
	s_cmp_lt_i32 s16, 0
	s_cbranch_scc1 .Lsb_fd_50
	s_mov_b32 s23, 0
	s_cmp_eq_u32 s16, 0
	s_cbranch_scc1 .Lsb_fl_51
	s_movk_i32 s23, 0x4000
	s_cmp_eq_u32 s16, s48
	s_cbranch_scc1 .Lsb_fl_51
	s_movk_i32 s23, 0x2000
	s_cmp_eq_u32 s16, s20
	s_cbranch_scc1 .Lsb_fl_51
	s_lshl_b32 s12, s16, 12
	s_mov_b32 s25, 1
	v_lshl_add_u64 v[192:193], v[166:167], 0, s[12:13]
	global_load_dwordx4 v[34:37], v[192:193], off
	global_load_dwordx4 v[38:41], v[192:193], off offset:1024
	global_load_dwordx4 v[42:45], v[192:193], off offset:2048
	global_load_dwordx4 v[46:49], v[192:193], off offset:3072
	v_lshl_add_u64 v[192:193], v[190:191], 0, s[12:13]
	global_load_dwordx4 v[50:53], v[192:193], off
	global_load_dwordx4 v[54:57], v[192:193], off offset:1024
	global_load_dwordx4 v[58:61], v[192:193], off offset:2048
	global_load_dwordx4 v[62:65], v[192:193], off offset:3072
	s_branch .Lsb_fd_50

.Lsb_wd_54:
	s_bfe_u32 s22, s17, 0x40000
	s_cmp_eq_u32 s22, 0
	s_cbranch_scc1 .Lsb_sg_55
	s_lshr_b32 s22, s17, 0
	v_lshrrev_b32_e64 v203, v165, s22
	v_and_b32_e32 v203, 1, v203
	v_cmp_eq_u32_e64 s[10:11], 1, v203
	s_setprio 1
	v_mfma_f32_16x16x32_fp8_fp8 v[66:69], v[212:213], v[144:145], 0
	v_mfma_f32_16x16x32_fp8_fp8 v[70:73], v[216:217], v[144:145], 0
	v_mfma_f32_16x16x32_fp8_fp8 v[74:77], v[220:221], v[144:145], 0
	v_mfma_f32_16x16x32_fp8_fp8 v[78:81], v[224:225], v[144:145], 0
	v_mfma_f32_16x16x32_fp8_fp8 v[66:69], v[214:215], v[146:147], v[66:69]
	v_mfma_f32_16x16x32_fp8_fp8 v[70:73], v[218:219], v[146:147], v[70:73]
	v_mfma_f32_16x16x32_fp8_fp8 v[74:77], v[222:223], v[146:147], v[74:77]
	v_mfma_f32_16x16x32_fp8_fp8 v[78:81], v[226:227], v[146:147], v[78:81]
	s_setprio 0
	v_cndmask_b32_e64 v205, v200, v158, s[10:11]
	s_cmp_lg_u32 s14, s48
	s_nop 6
	s_cbranch_scc1 .Lsb_nm_56
	v_sub_u32_e32 v244, v206, v187
	v_cmp_gt_i32_e32 vcc, 0, v244
	v_cmp_gt_i32_e64 s[22:23], 1, v244
	s_nop 0
	v_cndmask_b32_e32 v66, v66, v199, vcc
	v_cndmask_b32_e64 v67, v67, v199, s[22:23]
	v_cmp_gt_i32_e32 vcc, 2, v244
	v_cmp_gt_i32_e64 s[22:23], 3, v244
	s_nop 0
	v_cndmask_b32_e32 v68, v68, v199, vcc
	v_cndmask_b32_e64 v69, v69, v199, s[22:23]
	v_sub_u32_e32 v244, v206, v187
	v_subrev_u32_e32 v244, 16, v244
	v_cmp_gt_i32_e32 vcc, 0, v244
	v_cmp_gt_i32_e64 s[22:23], 1, v244
	s_nop 0
	v_cndmask_b32_e32 v70, v70, v199, vcc
	v_cndmask_b32_e64 v71, v71, v199, s[22:23]
	v_cmp_gt_i32_e32 vcc, 2, v244
	v_cmp_gt_i32_e64 s[22:23], 3, v244
	s_nop 0
	v_cndmask_b32_e32 v72, v72, v199, vcc
	v_cndmask_b32_e64 v73, v73, v199, s[22:23]
	v_sub_u32_e32 v244, v206, v187
	v_subrev_u32_e32 v244, 32, v244
	v_cmp_gt_i32_e32 vcc, 0, v244
	v_cmp_gt_i32_e64 s[22:23], 1, v244
	s_nop 0
	v_cndmask_b32_e32 v74, v74, v199, vcc
	v_cndmask_b32_e64 v75, v75, v199, s[22:23]
	v_cmp_gt_i32_e32 vcc, 2, v244
	v_cmp_gt_i32_e64 s[22:23], 3, v244
	s_nop 0
	v_cndmask_b32_e32 v76, v76, v199, vcc
	v_cndmask_b32_e64 v77, v77, v199, s[22:23]
	v_sub_u32_e32 v244, v206, v187
	v_subrev_u32_e32 v244, 48, v244
	v_cmp_gt_i32_e32 vcc, 0, v244
	v_cmp_gt_i32_e64 s[22:23], 1, v244
	s_nop 0
	v_cndmask_b32_e32 v78, v78, v199, vcc
	v_cndmask_b32_e64 v79, v79, v199, s[22:23]
	v_cmp_gt_i32_e32 vcc, 2, v244
	v_cmp_gt_i32_e64 s[22:23], 3, v244
	s_nop 0
	v_cndmask_b32_e32 v80, v80, v199, vcc
	v_cndmask_b32_e64 v81, v81, v199, s[22:23]

.Lsb_nr_57:
	s_mov_b32 s22, 0x3e38aa3b
	v_fma_f32 v66, v66, s22, -v205
	v_fma_f32 v67, v67, s22, -v205
	v_fma_f32 v68, v68, s22, -v205
	v_fma_f32 v69, v69, s22, -v205
	v_fma_f32 v70, v70, s22, -v205
	v_fma_f32 v71, v71, s22, -v205
	v_fma_f32 v72, v72, s22, -v205
	v_fma_f32 v73, v73, s22, -v205
	v_fma_f32 v74, v74, s22, -v205
	v_fma_f32 v75, v75, s22, -v205
	v_fma_f32 v76, v76, s22, -v205
	v_fma_f32 v77, v77, s22, -v205
	v_fma_f32 v78, v78, s22, -v205
	v_fma_f32 v79, v79, s22, -v205
	v_fma_f32 v80, v80, s22, -v205
	v_fma_f32 v81, v81, s22, -v205
	v_exp_f32_e32 v66, v66
	v_exp_f32_e32 v67, v67
	v_exp_f32_e32 v68, v68
	v_exp_f32_e32 v69, v69
	v_exp_f32_e32 v70, v70
	v_exp_f32_e32 v71, v71
	v_exp_f32_e32 v72, v72
	v_exp_f32_e32 v73, v73
	v_exp_f32_e32 v74, v74
	v_exp_f32_e32 v75, v75
	v_exp_f32_e32 v76, v76
	v_exp_f32_e32 v77, v77
	v_exp_f32_e32 v78, v78
	v_exp_f32_e32 v79, v79
	v_exp_f32_e32 v80, v80
	v_exp_f32_e32 v81, v81
	v_add_f32_e32 v244, v66, v70
	v_add_f32_e32 v245, v67, v71
	v_add_f32_e32 v246, v68, v72
	v_add_f32_e32 v247, v69, v73
	v_add_f32_e32 v248, v74, v78
	v_add_f32_e32 v249, v75, v79
	v_add_f32_e32 v250, v76, v80
	v_add_f32_e32 v251, v77, v81
	v_add_f32_e32 v244, v244, v248
	v_add_f32_e32 v245, v245, v249
	v_add_f32_e32 v246, v246, v250
	v_add_f32_e32 v247, v247, v251
	v_cvt_pk_fp8_f32 v154, v66, v67
	v_cvt_pk_fp8_f32 v155, v70, v71
	v_cvt_pk_fp8_f32 v156, v74, v75
	v_cvt_pk_fp8_f32 v157, v78, v79
	v_add_f32_e32 v244, v244, v245
	v_cvt_pk_fp8_f32 v154, v68, v69 op_sel:[0,0,1]
	v_cvt_pk_fp8_f32 v155, v72, v73 op_sel:[0,0,1]
	v_cvt_pk_fp8_f32 v156, v76, v77 op_sel:[0,0,1]
	v_cvt_pk_fp8_f32 v157, v80, v81 op_sel:[0,0,1]
	v_add_f32_e32 v246, v246, v247
	v_add_f32_e32 v244, v244, v246
	v_add_f32_e32 v159, v159, v244
	s_setprio 1
	v_mfma_f32_16x16x32_fp8_fp8 v[102:105], v[228:229], v[154:155], v[102:105]
	v_mfma_f32_16x16x32_fp8_fp8 v[106:109], v[232:233], v[154:155], v[106:109]
	v_mfma_f32_16x16x32_fp8_fp8 v[110:113], v[236:237], v[154:155], v[110:113]
	v_mfma_f32_16x16x32_fp8_fp8 v[114:117], v[240:241], v[154:155], v[114:117]
	v_mfma_f32_16x16x32_fp8_fp8 v[102:105], v[230:231], v[156:157], v[102:105]
	v_mfma_f32_16x16x32_fp8_fp8 v[106:109], v[234:235], v[156:157], v[106:109]
	v_mfma_f32_16x16x32_fp8_fp8 v[110:113], v[238:239], v[156:157], v[110:113]
	v_mfma_f32_16x16x32_fp8_fp8 v[114:117], v[242:243], v[156:157], v[114:117]
	s_setprio 0
.Lsb_sg_55:
	s_bfe_u32 s22, s17, 0x40004
	s_cmp_eq_u32 s22, 0
	s_cbranch_scc1 .Lsb_sg_58
	s_lshr_b32 s22, s17, 4
	v_lshrrev_b32_e64 v203, v165, s22
	v_and_b32_e32 v203, 1, v203
	v_cmp_eq_u32_e64 s[10:11], 1, v203
	s_setprio 1
	v_mfma_f32_16x16x32_fp8_fp8 v[66:69], v[212:213], v[150:151], 0
	v_mfma_f32_16x16x32_fp8_fp8 v[70:73], v[216:217], v[150:151], 0
	v_mfma_f32_16x16x32_fp8_fp8 v[74:77], v[220:221], v[150:151], 0
	v_mfma_f32_16x16x32_fp8_fp8 v[78:81], v[224:225], v[150:151], 0
	v_mfma_f32_16x16x32_fp8_fp8 v[66:69], v[214:215], v[152:153], v[66:69]
	v_mfma_f32_16x16x32_fp8_fp8 v[70:73], v[218:219], v[152:153], v[70:73]
	v_mfma_f32_16x16x32_fp8_fp8 v[74:77], v[222:223], v[152:153], v[74:77]
	v_mfma_f32_16x16x32_fp8_fp8 v[78:81], v[226:227], v[152:153], v[78:81]
	s_setprio 0
	v_cndmask_b32_e64 v205, v200, v162, s[10:11]
	s_cmp_lg_u32 s14, s48
	s_nop 6
	s_cbranch_scc1 .Lsb_nm_59
	v_sub_u32_e32 v244, v206, v187
	v_subrev_u32_e32 v244, -4, v244
	v_cmp_gt_i32_e32 vcc, 0, v244
	v_cmp_gt_i32_e64 s[22:23], 1, v244
	s_nop 0
	v_cndmask_b32_e32 v66, v66, v199, vcc
	v_cndmask_b32_e64 v67, v67, v199, s[22:23]
	v_cmp_gt_i32_e32 vcc, 2, v244
	v_cmp_gt_i32_e64 s[22:23], 3, v244
	s_nop 0
	v_cndmask_b32_e32 v68, v68, v199, vcc
	v_cndmask_b32_e64 v69, v69, v199, s[22:23]
	v_sub_u32_e32 v244, v206, v187
	v_subrev_u32_e32 v244, 12, v244
	v_cmp_gt_i32_e32 vcc, 0, v244
	v_cmp_gt_i32_e64 s[22:23], 1, v244
	s_nop 0
	v_cndmask_b32_e32 v70, v70, v199, vcc
	v_cndmask_b32_e64 v71, v71, v199, s[22:23]
	v_cmp_gt_i32_e32 vcc, 2, v244
	v_cmp_gt_i32_e64 s[22:23], 3, v244
	s_nop 0
	v_cndmask_b32_e32 v72, v72, v199, vcc
	v_cndmask_b32_e64 v73, v73, v199, s[22:23]
	v_sub_u32_e32 v244, v206, v187
	v_subrev_u32_e32 v244, 28, v244
	v_cmp_gt_i32_e32 vcc, 0, v244
	v_cmp_gt_i32_e64 s[22:23], 1, v244
	s_nop 0
	v_cndmask_b32_e32 v74, v74, v199, vcc
	v_cndmask_b32_e64 v75, v75, v199, s[22:23]
	v_cmp_gt_i32_e32 vcc, 2, v244
	v_cmp_gt_i32_e64 s[22:23], 3, v244
	s_nop 0
	v_cndmask_b32_e32 v76, v76, v199, vcc
	v_cndmask_b32_e64 v77, v77, v199, s[22:23]
	v_sub_u32_e32 v244, v206, v187
	v_subrev_u32_e32 v244, 44, v244
	v_cmp_gt_i32_e32 vcc, 0, v244
	v_cmp_gt_i32_e64 s[22:23], 1, v244
	s_nop 0
	v_cndmask_b32_e32 v78, v78, v199, vcc
	v_cndmask_b32_e64 v79, v79, v199, s[22:23]
	v_cmp_gt_i32_e32 vcc, 2, v244
	v_cmp_gt_i32_e64 s[22:23], 3, v244
	s_nop 0
	v_cndmask_b32_e32 v80, v80, v199, vcc
	v_cndmask_b32_e64 v81, v81, v199, s[22:23]

.Lsb_nr_60:
	s_mov_b32 s22, 0x3e38aa3b
	v_fma_f32 v66, v66, s22, -v205
	v_fma_f32 v67, v67, s22, -v205
	v_fma_f32 v68, v68, s22, -v205
	v_fma_f32 v69, v69, s22, -v205
	v_fma_f32 v70, v70, s22, -v205
	v_fma_f32 v71, v71, s22, -v205
	v_fma_f32 v72, v72, s22, -v205
	v_fma_f32 v73, v73, s22, -v205
	v_fma_f32 v74, v74, s22, -v205
	v_fma_f32 v75, v75, s22, -v205
	v_fma_f32 v76, v76, s22, -v205
	v_fma_f32 v77, v77, s22, -v205
	v_fma_f32 v78, v78, s22, -v205
	v_fma_f32 v79, v79, s22, -v205
	v_fma_f32 v80, v80, s22, -v205
	v_fma_f32 v81, v81, s22, -v205
	v_exp_f32_e32 v66, v66
	v_exp_f32_e32 v67, v67
	v_exp_f32_e32 v68, v68
	v_exp_f32_e32 v69, v69
	v_exp_f32_e32 v70, v70
	v_exp_f32_e32 v71, v71
	v_exp_f32_e32 v72, v72
	v_exp_f32_e32 v73, v73
	v_exp_f32_e32 v74, v74
	v_exp_f32_e32 v75, v75
	v_exp_f32_e32 v76, v76
	v_exp_f32_e32 v77, v77
	v_exp_f32_e32 v78, v78
	v_exp_f32_e32 v79, v79
	v_exp_f32_e32 v80, v80
	v_exp_f32_e32 v81, v81
	v_add_f32_e32 v244, v66, v70
	v_add_f32_e32 v245, v67, v71
	v_add_f32_e32 v246, v68, v72
	v_add_f32_e32 v247, v69, v73
	v_add_f32_e32 v248, v74, v78
	v_add_f32_e32 v249, v75, v79
	v_add_f32_e32 v250, v76, v80
	v_add_f32_e32 v251, v77, v81
	v_add_f32_e32 v244, v244, v248
	v_add_f32_e32 v245, v245, v249
	v_add_f32_e32 v246, v246, v250
	v_add_f32_e32 v247, v247, v251
	v_cvt_pk_fp8_f32 v154, v66, v67
	v_cvt_pk_fp8_f32 v155, v70, v71
	v_cvt_pk_fp8_f32 v156, v74, v75
	v_cvt_pk_fp8_f32 v157, v78, v79
	v_add_f32_e32 v244, v244, v245
	v_cvt_pk_fp8_f32 v154, v68, v69 op_sel:[0,0,1]
	v_cvt_pk_fp8_f32 v155, v72, v73 op_sel:[0,0,1]
	v_cvt_pk_fp8_f32 v156, v76, v77 op_sel:[0,0,1]
	v_cvt_pk_fp8_f32 v157, v80, v81 op_sel:[0,0,1]
	v_add_f32_e32 v246, v246, v247
	v_add_f32_e32 v244, v244, v246
	v_add_f32_e32 v163, v163, v244
	s_setprio 1
	v_mfma_f32_16x16x32_fp8_fp8 v[118:121], v[228:229], v[154:155], v[118:121]
	v_mfma_f32_16x16x32_fp8_fp8 v[122:125], v[232:233], v[154:155], v[122:125]
	v_mfma_f32_16x16x32_fp8_fp8 v[136:139], v[236:237], v[154:155], v[136:139]
	v_mfma_f32_16x16x32_fp8_fp8 v[140:143], v[240:241], v[154:155], v[140:143]
	v_mfma_f32_16x16x32_fp8_fp8 v[118:121], v[230:231], v[156:157], v[118:121]
	v_mfma_f32_16x16x32_fp8_fp8 v[122:125], v[234:235], v[156:157], v[122:125]
	v_mfma_f32_16x16x32_fp8_fp8 v[136:139], v[238:239], v[156:157], v[136:139]
	v_mfma_f32_16x16x32_fp8_fp8 v[140:143], v[242:243], v[156:157], v[140:143]
	s_setprio 0
.Lsb_sg_58:
	s_mov_b32 s14, s15
	s_mov_b32 s15, s16
	s_mov_b32 s17, s18
	s_mov_b32 s18, s19
	s_mov_b32 s24, s25
	s_branch .Lsb_step0
.Lsb_exit:
	s_waitcnt vmcnt(0)
	ds_bpermute_b32 v203, v197, v159
	s_waitcnt lgkmcnt(0)
	v_add_f32_e32 v159, v159, v203
	ds_bpermute_b32 v203, v198, v159
	s_waitcnt lgkmcnt(0)
	v_add_f32_e32 v159, v159, v203
	v_div_scale_f32 v244, s[22:23], v159, v159, v208
	v_rcp_f32_e32 v245, v244
	s_nop 0
	v_fma_f32 v246, -v244, v245, 1.0
	v_fmac_f32_e32 v245, v246, v245
	v_div_scale_f32 v246, vcc, v208, v159, v208
	v_mul_f32_e32 v247, v246, v245
	v_fma_f32 v248, -v244, v247, v246
	v_fmac_f32_e32 v247, v248, v245
	v_fma_f32 v244, -v244, v247, v246
	v_div_fmas_f32 v244, v244, v245, v247
	v_div_fixup_f32 v209, v244, v159, v208
	ds_read2_b64 v[244:247], v207 offset0:0 offset1:4
	s_waitcnt lgkmcnt(0)
	v_lshlrev_b32_e32 v248, 16, v244
	v_and_b32_e32 v249, 0xffff0000, v244
	v_lshlrev_b32_e32 v250, 16, v245
	v_and_b32_e32 v251, 0xffff0000, v245
	v_fma_f32 v248, v102, v209, v248
	v_fma_f32 v249, v103, v209, v249
	v_fma_f32 v250, v104, v209, v250
	v_fma_f32 v251, v105, v209, v251
	v_cvt_pk_bf16_f32 v244, v248, v249
	v_cvt_pk_bf16_f32 v245, v250, v251
	v_lshlrev_b32_e32 v248, 16, v246
	v_and_b32_e32 v249, 0xffff0000, v246
	v_lshlrev_b32_e32 v250, 16, v247
	v_and_b32_e32 v251, 0xffff0000, v247
	v_fma_f32 v248, v106, v209, v248
	v_fma_f32 v249, v107, v209, v249
	v_fma_f32 v250, v108, v209, v250
	v_fma_f32 v251, v109, v209, v251
	v_cvt_pk_bf16_f32 v246, v248, v249
	v_cvt_pk_bf16_f32 v247, v250, v251
	ds_write2_b64 v207, v[244:245], v[246:247] offset0:0 offset1:4
	ds_read2_b64 v[244:247], v207 offset0:8 offset1:12
	s_waitcnt lgkmcnt(0)
	v_lshlrev_b32_e32 v248, 16, v244
	v_and_b32_e32 v249, 0xffff0000, v244
	v_lshlrev_b32_e32 v250, 16, v245
	v_and_b32_e32 v251, 0xffff0000, v245
	v_fma_f32 v248, v110, v209, v248
	v_fma_f32 v249, v111, v209, v249
	v_fma_f32 v250, v112, v209, v250
	v_fma_f32 v251, v113, v209, v251
	v_cvt_pk_bf16_f32 v244, v248, v249
	v_cvt_pk_bf16_f32 v245, v250, v251
	v_lshlrev_b32_e32 v248, 16, v246
	v_and_b32_e32 v249, 0xffff0000, v246
	v_lshlrev_b32_e32 v250, 16, v247
	v_and_b32_e32 v251, 0xffff0000, v247
	v_fma_f32 v248, v114, v209, v248
	v_fma_f32 v249, v115, v209, v249
	v_fma_f32 v250, v116, v209, v250
	v_fma_f32 v251, v117, v209, v251
	v_cvt_pk_bf16_f32 v246, v248, v249
	v_cvt_pk_bf16_f32 v247, v250, v251
	ds_write2_b64 v207, v[244:245], v[246:247] offset0:8 offset1:12
	v_add_u32_e32 v207, 0x800, v207
	ds_bpermute_b32 v203, v197, v163
	s_waitcnt lgkmcnt(0)
	v_add_f32_e32 v163, v163, v203
	ds_bpermute_b32 v203, v198, v163
	s_waitcnt lgkmcnt(0)
	v_add_f32_e32 v163, v163, v203
	v_div_scale_f32 v244, s[22:23], v163, v163, v148
	v_rcp_f32_e32 v245, v244
	s_nop 0
	v_fma_f32 v246, -v244, v245, 1.0
	v_fmac_f32_e32 v245, v246, v245
	v_div_scale_f32 v246, vcc, v148, v163, v148
	v_mul_f32_e32 v247, v246, v245
	v_fma_f32 v248, -v244, v247, v246
	v_fmac_f32_e32 v247, v248, v245
	v_fma_f32 v244, -v244, v247, v246
	v_div_fmas_f32 v244, v244, v245, v247
	v_div_fixup_f32 v209, v244, v163, v148
	ds_read2_b64 v[244:247], v207 offset0:0 offset1:4
	s_waitcnt lgkmcnt(0)
	v_lshlrev_b32_e32 v248, 16, v244
	v_and_b32_e32 v249, 0xffff0000, v244
	v_lshlrev_b32_e32 v250, 16, v245
	v_and_b32_e32 v251, 0xffff0000, v245
	v_fma_f32 v248, v118, v209, v248
	v_fma_f32 v249, v119, v209, v249
	v_fma_f32 v250, v120, v209, v250
	v_fma_f32 v251, v121, v209, v251
	v_cvt_pk_bf16_f32 v244, v248, v249
	v_cvt_pk_bf16_f32 v245, v250, v251
	v_lshlrev_b32_e32 v248, 16, v246
	v_and_b32_e32 v249, 0xffff0000, v246
	v_lshlrev_b32_e32 v250, 16, v247
	v_and_b32_e32 v251, 0xffff0000, v247
	v_fma_f32 v248, v122, v209, v248
	v_fma_f32 v249, v123, v209, v249
	v_fma_f32 v250, v124, v209, v250
	v_fma_f32 v251, v125, v209, v251
	v_cvt_pk_bf16_f32 v246, v248, v249
	v_cvt_pk_bf16_f32 v247, v250, v251
	ds_write2_b64 v207, v[244:245], v[246:247] offset0:0 offset1:4
	ds_read2_b64 v[244:247], v207 offset0:8 offset1:12
	s_waitcnt lgkmcnt(0)
	v_lshlrev_b32_e32 v248, 16, v244
	v_and_b32_e32 v249, 0xffff0000, v244
	v_lshlrev_b32_e32 v250, 16, v245
	v_and_b32_e32 v251, 0xffff0000, v245
	v_fma_f32 v248, v136, v209, v248
	v_fma_f32 v249, v137, v209, v249
	v_fma_f32 v250, v138, v209, v250
	v_fma_f32 v251, v139, v209, v251
	v_cvt_pk_bf16_f32 v244, v248, v249
	v_cvt_pk_bf16_f32 v245, v250, v251
	v_lshlrev_b32_e32 v248, 16, v246
	v_and_b32_e32 v249, 0xffff0000, v246
	v_lshlrev_b32_e32 v250, 16, v247
	v_and_b32_e32 v251, 0xffff0000, v247
	v_fma_f32 v248, v140, v209, v248
	v_fma_f32 v249, v141, v209, v249
	v_fma_f32 v250, v142, v209, v250
	v_fma_f32 v251, v143, v209, v251
	v_cvt_pk_bf16_f32 v246, v248, v249
	v_cvt_pk_bf16_f32 v247, v250, v251
	ds_write2_b64 v207, v[244:245], v[246:247] offset0:8 offset1:12
